# P1 RMSNorm with 2 row buffers (1 row ahead) instead of 4 on top of the skip-127 best: less memory-level parallelism in the bandwidth-bound phase
# speedup vs baseline: 1.0203x; 1.0031x over previous
.LBB0_107:
	s_or_b64 exec, exec, s[4:5]
	s_load_dwordx16 s[36:51], s[0:1], 0x40
	s_cmpk_gt_i32 s64, 0x7fff
	v_lshlrev_b32_e32 v128, 2, v129
	v_mbcnt_lo_u32_b32 v165, -1, 0
	s_waitcnt lgkmcnt(0)
	s_barrier
	s_cbranch_scc1 .LBB0_110
	v_lshlrev_b32_e32 v120, 2, v128
	v_lshlrev_b32_e32 v121, 3, v129
	s_mov_b32 s65, s64
	s_lshl_b32 s13, s12, 12
	s_lshl_b32 s98, s12, 11
	s_lshl_b32 s0, s64, 12
	s_add_u32 s0, s16, s0
	s_addc_u32 s1, s17, 0
	s_lshl_b32 s4, s64, 11
	s_add_u32 s4, s62, s4
	s_addc_u32 s5, s63, 0
	s_add_u32 s4, s4, 0x2800000
	s_addc_u32 s5, s5, 0
	s_mov_b32 s99, -1
	s_mov_b32 s18, s0
	s_mov_b32 s19, s1
	global_load_dwordx4 v[0:3], v120, s[18:19] offset:0
	global_load_dwordx4 v[4:7], v120, s[18:19] offset:1024
	global_load_dwordx4 v[8:11], v120, s[18:19] offset:2048
	global_load_dwordx4 v[12:15], v120, s[18:19] offset:3072
	global_load_dwordx4 v[64:67], v120, s[24:25] offset:0
	global_load_dwordx4 v[68:71], v120, s[24:25] offset:1024
	global_load_dwordx4 v[72:75], v120, s[24:25] offset:2048
	global_load_dwordx4 v[76:79], v120, s[24:25] offset:3072
.Lp1_row_r0:
	s_lshr_b32 s100, s65, 13
	s_cmp_eq_u32 s100, s99
	s_cbranch_scc1 .Lp1_nov_r0
	s_mov_b32 s99, s100
	s_mul_i32 s100, s100, 0x6000
	s_add_u32 s8, s6, s100
	s_addc_u32 s9, s7, 0
	s_add_u32 s18, s8, 0x1000
	s_addc_u32 s19, s9, 0
	global_load_dwordx4 v[80:83], v120, s[18:19] offset:0
	global_load_dwordx4 v[84:87], v120, s[18:19] offset:1024
	global_load_dwordx4 v[88:91], v120, s[18:19] offset:2048
	global_load_dwordx4 v[92:95], v120, s[18:19] offset:3072
	global_load_dwordx4 v[96:99], v120, s[8:9] offset:0
	global_load_dwordx4 v[100:103], v120, s[8:9] offset:1024
	global_load_dwordx4 v[104:107], v120, s[8:9] offset:2048
	global_load_dwordx4 v[108:111], v120, s[8:9] offset:3072
	s_mov_b32 s101, 1
	s_branch .Lp1_pf_r0

.Lp1_pf_r0:
	s_mul_i32 s100, s12, 1
	s_add_u32 s100, s65, s100
	s_cmp_lt_u32 s100, 0x8000
	s_cbranch_scc1 .Lp1_adv_r0
	s_mov_b32 s18, s0
	s_mov_b32 s19, s1
	s_branch .Lp1_ld_r0
.Lp1_adv_r0:
	s_mul_i32 s18, s13, 1
	s_add_u32 s18, s0, s18
	s_addc_u32 s19, s1, 0
.Lp1_ld_r0:
	global_load_dwordx4 v[16:19], v120, s[18:19] offset:0
	global_load_dwordx4 v[20:23], v120, s[18:19] offset:1024
	global_load_dwordx4 v[24:27], v120, s[18:19] offset:2048
	global_load_dwordx4 v[28:31], v120, s[18:19] offset:3072
	s_cmp_eq_u32 s101, 0
	s_cbranch_scc1 .Lp1_w8_r0
	s_waitcnt vmcnt(4)
	v_add_f32_e32 v80, 1.0, v80
	v_add_f32_e32 v81, 1.0, v81
	v_add_f32_e32 v82, 1.0, v82
	v_add_f32_e32 v83, 1.0, v83
	v_add_f32_e32 v84, 1.0, v84
	v_add_f32_e32 v85, 1.0, v85
	v_add_f32_e32 v86, 1.0, v86
	v_add_f32_e32 v87, 1.0, v87
	v_add_f32_e32 v88, 1.0, v88
	v_add_f32_e32 v89, 1.0, v89
	v_add_f32_e32 v90, 1.0, v90
	v_add_f32_e32 v91, 1.0, v91
	v_add_f32_e32 v92, 1.0, v92
	v_add_f32_e32 v93, 1.0, v93
	v_add_f32_e32 v94, 1.0, v94
	v_add_f32_e32 v95, 1.0, v95
	s_branch .Lp1_go_r0

.Lp1_adv_r1:
	s_mul_i32 s18, s13, 1
	s_add_u32 s18, s0, s18
	s_addc_u32 s19, s1, 0
.Lp1_ld_r1:
	global_load_dwordx4 v[0:3], v120, s[18:19] offset:0
	global_load_dwordx4 v[4:7], v120, s[18:19] offset:1024
	global_load_dwordx4 v[8:11], v120, s[18:19] offset:2048
	global_load_dwordx4 v[12:15], v120, s[18:19] offset:3072
	s_cmp_eq_u32 s101, 0
	s_cbranch_scc1 .Lp1_w8_r1
	s_waitcnt vmcnt(4)
	v_add_f32_e32 v80, 1.0, v80
	v_add_f32_e32 v81, 1.0, v81
	v_add_f32_e32 v82, 1.0, v82
	v_add_f32_e32 v83, 1.0, v83
	v_add_f32_e32 v84, 1.0, v84
	v_add_f32_e32 v85, 1.0, v85
	v_add_f32_e32 v86, 1.0, v86
	v_add_f32_e32 v87, 1.0, v87
	v_add_f32_e32 v88, 1.0, v88
	v_add_f32_e32 v89, 1.0, v89
	v_add_f32_e32 v90, 1.0, v90
	v_add_f32_e32 v91, 1.0, v91
	v_add_f32_e32 v92, 1.0, v92
	v_add_f32_e32 v93, 1.0, v93
	v_add_f32_e32 v94, 1.0, v94
	v_add_f32_e32 v95, 1.0, v95
	s_branch .Lp1_go_r1

.Lp1_go_r1:
	v_mul_f32_e32 v122, v16, v16
	v_fmac_f32_e32 v122, v17, v17
	v_fmac_f32_e32 v122, v18, v18
	v_fmac_f32_e32 v122, v19, v19
	v_fmac_f32_e32 v122, v20, v20
	v_fmac_f32_e32 v122, v21, v21
	v_fmac_f32_e32 v122, v22, v22
	v_fmac_f32_e32 v122, v23, v23
	v_fmac_f32_e32 v122, v24, v24
	v_fmac_f32_e32 v122, v25, v25
	v_fmac_f32_e32 v122, v26, v26
	v_fmac_f32_e32 v122, v27, v27
	v_fmac_f32_e32 v122, v28, v28
	v_fmac_f32_e32 v122, v29, v29
	v_fmac_f32_e32 v122, v30, v30
	v_fmac_f32_e32 v122, v31, v31
	s_nop 1
	v_add_f32_dpp v124, v122, v122 quad_perm:[1,0,3,2] row_mask:0xf bank_mask:0xf
	s_nop 1
	v_add_f32_dpp v122, v124, v124 quad_perm:[2,3,0,1] row_mask:0xf bank_mask:0xf
	s_nop 1
	v_add_f32_dpp v124, v122, v122 row_half_mirror row_mask:0xf bank_mask:0xf
	s_nop 1
	v_add_f32_dpp v122, v124, v124 row_mirror row_mask:0xf bank_mask:0xf
	s_nop 1
	v_readlane_b32 s100, v122, 0
	v_readlane_b32 s101, v122, 16
	v_readlane_b32 s18, v122, 32
	v_readlane_b32 s19, v122, 48
	s_nop 1
	v_mov_b32_e32 v124, s100
	v_add_f32_e32 v124, s101, v124
	v_mov_b32_e32 v122, s18
	v_add_f32_e32 v122, s19, v122
	v_add_f32_e32 v124, v124, v122
	v_mov_b32_e32 v122, 0x358637bd
	v_fmamk_f32 v124, v124, 0x3a800000, v122
	v_rsq_f32_e32 v123, v124
	s_nop 0
	v_mul_f32_e32 v16, v123, v16
	v_mul_f32_e32 v17, v123, v17
	v_mul_f32_e32 v18, v123, v18
	v_mul_f32_e32 v19, v123, v19
	v_mul_f32_e32 v20, v123, v20
	v_mul_f32_e32 v21, v123, v21
	v_mul_f32_e32 v22, v123, v22
	v_mul_f32_e32 v23, v123, v23
	v_mul_f32_e32 v24, v123, v24
	v_mul_f32_e32 v25, v123, v25
	v_mul_f32_e32 v26, v123, v26
	v_mul_f32_e32 v27, v123, v27
	v_mul_f32_e32 v28, v123, v28
	v_mul_f32_e32 v29, v123, v29
	v_mul_f32_e32 v30, v123, v30
	v_mul_f32_e32 v31, v123, v31
	v_mul_f32_e32 v16, v64, v16
	v_mul_f32_e32 v17, v65, v17
	v_mul_f32_e32 v18, v66, v18
	v_mul_f32_e32 v19, v67, v19
	v_mul_f32_e32 v20, v68, v20
	v_mul_f32_e32 v21, v69, v21
	v_mul_f32_e32 v22, v70, v22
	v_mul_f32_e32 v23, v71, v23
	v_mul_f32_e32 v24, v72, v24
	v_mul_f32_e32 v25, v73, v25
	v_mul_f32_e32 v26, v74, v26
	v_mul_f32_e32 v27, v75, v27
	v_mul_f32_e32 v28, v76, v28
	v_mul_f32_e32 v29, v77, v29
	v_mul_f32_e32 v30, v78, v30
	v_mul_f32_e32 v31, v79, v31
	v_fma_f32 v16, v80, v16, v96
	v_fma_f32 v17, v81, v17, v97
	v_fma_f32 v18, v82, v18, v98
	v_fma_f32 v19, v83, v19, v99
	v_fma_f32 v20, v84, v20, v100
	v_fma_f32 v21, v85, v21, v101
	v_fma_f32 v22, v86, v22, v102
	v_fma_f32 v23, v87, v23, v103
	v_fma_f32 v24, v88, v24, v104
	v_fma_f32 v25, v89, v25, v105
	v_fma_f32 v26, v90, v26, v106
	v_fma_f32 v27, v91, v27, v107
	v_fma_f32 v28, v92, v28, v108
	v_fma_f32 v29, v93, v29, v109
	v_fma_f32 v30, v94, v30, v110
	v_fma_f32 v31, v95, v31, v111
	v_cvt_pk_bf16_f32 v112, v16, v17
	v_cvt_pk_bf16_f32 v113, v18, v19
	v_cvt_pk_bf16_f32 v114, v20, v21
	v_cvt_pk_bf16_f32 v115, v22, v23
	v_cvt_pk_bf16_f32 v116, v24, v25
	v_cvt_pk_bf16_f32 v117, v26, v27
	v_cvt_pk_bf16_f32 v118, v28, v29
	v_cvt_pk_bf16_f32 v119, v30, v31
	global_store_dwordx2 v121, v[112:113], s[4:5] offset:0
	global_store_dwordx2 v121, v[114:115], s[4:5] offset:512
	global_store_dwordx2 v121, v[116:117], s[4:5] offset:1024
	global_store_dwordx2 v121, v[118:119], s[4:5] offset:1536
	s_add_u32 s65, s65, s12
	s_add_u32 s0, s0, s13
	s_addc_u32 s1, s1, 0
	s_add_u32 s4, s4, s98
	s_addc_u32 s5, s5, 0
	s_cmp_lt_u32 s65, 0x8000
	s_cbranch_scc1 .Lp1_row_r0
